# attention K/V global prefetch depth raised from 2 to 4 tiles (loop unrolled by 4, four K/V register sets)
# baseline (speedup 1.0000x reference)
; #define LAS __attribute__((address_space(3)))
; __device__ __forceinline__ int fresh_tid() { int t = threadIdx.x; asm volatile("" : "+v"(t)); return t; }
; __device__ __forceinline__ void attn_stage(LAS unsigned char* lds, int buf, const u32x4& kreg, const u32x4& vreg) {
;     const int tid = fresh_tid(), key = tid >> 3, ch = tid & 7;
;     *(LAS u32x4*)(lds + AT_K + buf * AT_KB + key * 144 + ch * 16) = kreg;
;     LAS bf16_t* vt = (LAS bf16_t*)(lds + AT_VT + buf * AT_VB) + (ch * 8) * 68 + key;
;     vt[0 * 68] = (bf16_t)(vreg.x & 0xffffu); vt[1 * 68] = (bf16_t)(vreg.x >> 16);
;     vt[2 * 68] = (bf16_t)(vreg.y & 0xffffu); vt[3 * 68] = (bf16_t)(vreg.y >> 16);
;     vt[4 * 68] = (bf16_t)(vreg.z & 0xffffu); vt[5 * 68] = (bf16_t)(vreg.z >> 16);
;     vt[6 * 68] = (bf16_t)(vreg.w & 0xffffu); vt[7 * 68] = (bf16_t)(vreg.w >> 16);
; }
; __device__ __forceinline__ void attn_unit(const AttnJob& J, LAS unsigned char* lds) {
;     ...
;     u32x4 kA, vA, kB, vB;
;     attn_load(J, 0, kA, vA);
;     if (J.NT > 1) attn_load(J, 1, kB, vB); else { kB = (u32x4){0u, 0u, 0u, 0u}; vB = kB; }
;     for (int t = 0; t < J.NT; t += 2) {
;         attn_stage(lds, 0, kA, vA);
;         __syncthreads();
;         if (t + 2 < J.NT) attn_load(J, t + 2, kA, vA);
.LBB0_645:
	s_mov_b32 s22, 0
	s_mov_b32 s26, 0
	s_mov_b32 s27, 0
	s_add_u32 s98, s8, 0x80000
	s_addc_u32 s99, s9, 0
	global_load_dwordx4 v[238:241], v158, s[98:99] offset:1024
	global_load_dwordx4 v[242:245], v158, s[98:99] offset:2048
	s_add_u32 s98, s8, 0xc0000
	s_addc_u32 s99, s9, 0
	global_load_dwordx4 v[246:249], v158, s[98:99] offset:1024
.Lslot_S0:
	s_waitcnt vmcnt(6)
	ds_write_b128 v156, v[82:85] offset:8448
	s_cmp_eq_u32 s22, 0
	s_cbranch_scc1 .LnoV_E
	ds_write_b16 v157, v160 offset:35584
	ds_write_b16_d16_hi v157, v160 offset:35720
	ds_write_b16 v157, v161 offset:35856
	ds_write_b16_d16_hi v157, v161 offset:35992
	ds_write_b16 v157, v162 offset:36128
	ds_write_b16_d16_hi v157, v162 offset:36264
	ds_write_b16 v157, v163 offset:36400
	ds_write_b16_d16_hi v157, v163 offset:36536
; __device__ __forceinline__ void attn_tile(int t, int buf, LAS unsigned char* lds, const bf16x8 (&qr)[4], float cq2, int qlo, int qpos, int q32, int hi,
;                                           float& mrun, float& lrun, f32x16& o0, f32x16& o1) {
;     const LAS float* c2s = (const LAS float*)(lds + AT_C2);
;     const LAS unsigned char* Kt = lds + AT_K + buf * AT_KB; const LAS unsigned char* Vt = lds + AT_VT + buf * AT_VB;
;     f32x16 s0, s1;
; #pragma unroll
;     for (int j = 0; j < 4; ++j) {
;         const f32x4 c0 = *(const LAS f32x4*)(c2s + 64 * t + 8 * j + 4 * hi), c1 = *(const LAS f32x4*)(c2s + 64 * t + 32 + 8 * j + 4 * hi);
; #pragma unroll
;         for (int e = 0; e < 4; ++e) { s0[4 * j + e] = c0[e]; s1[4 * j + e] = c1[e]; }
;     }
; #pragma unroll
;     for (int d0 = 0; d0 < 4; ++d0) {
;         const bf16x8 k0 = *(const LAS bf16x8*)(Kt + q32 * 144 + d0 * 32 + hi * 16);
;         const bf16x8 k1 = *(const LAS bf16x8*)(Kt + (32 + q32) * 144 + d0 * 32 + hi * 16);
;         s0 = __builtin_amdgcn_mfma_f32_32x32x16_bf16(k0, qr[d0], s0, 0, 0, 0);
;         s1 = __builtin_amdgcn_mfma_f32_32x32x16_bf16(k1, qr[d0], s1, 0, 0, 0);
;     }
;     if (64 * t + 63 > qlo) {
; #pragma unroll
;         for (int r = 0; r < 16; ++r) { const int kv = 64 * t + crow(r, hi); if (kv > qpos) s0[r] = -INFINITY; if (kv + 32 > qpos) s1[r] = -INFINITY; }
;     }
;     float mx = fmaxf(s0[0], s1[0]);
; #pragma unroll
;     for (int r = 1; r < 16; ++r) mx = fmaxf(mx, fmaxf(s0[r], s1[r]));
;     mx = fmaxf(mx, __shfl_xor(mx, 32));
;     const float mnew = fmaxf(mrun, mx);
;     if (__any(mnew > mrun)) {
;         const float alpha = fexp2(mrun - mnew); lrun *= alpha;
; #pragma unroll
;         for (int r = 0; r < 16; ++r) { o0[r] *= alpha; o1[r] *= alpha; }
;     }
;     mrun = mnew;
;     f32x2 ls2 = (f32x2){0.f, 0.f};
; #pragma unroll
;     for (int r = 0; r < 16; r += 2) {
;         const f32x2 d0 = (f32x2){s0[r], s0[r + 1]} - mnew, d1 = (f32x2){s1[r], s1[r + 1]} - mnew;
; __device__ __forceinline__ void attn_unit(const AttnJob& J, LAS unsigned char* lds) {
;     ...
;     for (int t = 0; t < J.NT; t += 2) {
;         attn_stage(lds, 0, kA, vA);
;         __syncthreads();
;         if (t + 2 < J.NT) attn_load(J, t + 2, kA, vA);
;         if (active && 64 * t <= qlo + 31) attn_tile(t, 0, lds, qr, cq2, qlo, qpos, q32, hi, mrun, lrun, o0, o1);
.LnoV_E:
	s_waitcnt lgkmcnt(0)
	s_barrier
	s_add_i32 s6, s22, 4
	s_lshl_b32 s6, s6, 18
	s_add_u32 s98, s8, s6
	s_addc_u32 s99, s9, 0
	global_load_dwordx4 v[82:85], v158, s[98:99] offset:1024
	s_sub_u32 s100, s98, 0x40000
	s_subb_u32 s101, s99, 0
	global_load_dwordx4 v[160:163], v158, s[100:101] offset:2048
	s_lshl_b32 s6, s22, 6
	s_cmp_le_i32 s6, s23
	s_cbranch_scc0 .Lnoproc_S0
	ds_read_b128 v[124:127], v112 offset:8448
	ds_read_b128 v[34:37], v111
	ds_read_b128 v[38:41], v111 offset:32
	ds_read_b128 v[42:45], v111 offset:64
	ds_read_b128 v[46:49], v111 offset:96
	ds_read_b128 v[128:131], v112 offset:13056
	ds_read_b128 v[50:53], v111 offset:128
	ds_read_b128 v[54:57], v111 offset:160
	ds_read_b128 v[58:61], v111 offset:192
	ds_read_b128 v[62:65], v111 offset:224
	ds_read_b128 v[132:135], v112 offset:8480
	ds_read_b128 v[136:139], v112 offset:13088
	ds_read_b128 v[140:143], v112 offset:8512
	ds_read_b128 v[144:147], v112 offset:13120
	s_cmp_eq_u32 s27, 0
	s_cbranch_scc1 .Lqkonly_S0
	v_sub_f32_e32 v206, v206, v114
	v_sub_f32_e32 v207, v207, v114
	v_sub_f32_e32 v208, v208, v114
	v_sub_f32_e32 v209, v209, v114
	v_sub_f32_e32 v210, v210, v114
	v_sub_f32_e32 v211, v211, v114
	v_sub_f32_e32 v212, v212, v114
	v_sub_f32_e32 v213, v213, v114
	v_exp_f32_e32 v206, v206
	v_exp_f32_e32 v207, v207
	v_exp_f32_e32 v208, v208
	v_exp_f32_e32 v209, v209
	v_exp_f32_e32 v210, v210
	v_exp_f32_e32 v211, v211
	v_exp_f32_e32 v212, v212
	v_exp_f32_e32 v213, v213
	v_cvt_pk_bf16_f32 v118, v206, v207
	v_cvt_pk_bf16_f32 v119, v208, v209
	v_cvt_pk_bf16_f32 v120, v210, v211
	v_cvt_pk_bf16_f32 v121, v212, v213
	v_add_f32_e32 v116, v206, v208
	v_add_f32_e32 v117, v207, v209
	v_add_f32_e32 v116, v116, v210
	v_add_f32_e32 v117, v117, v211
	v_add_f32_e32 v116, v116, v212
	v_add_f32_e32 v117, v117, v213
	s_waitcnt lgkmcnt(9)
	v_mfma_f32_32x32x16_bf16 v[34:49], v[124:127], v[78:81], v[34:49]
	ds_read_b128 v[148:151], v112 offset:8544
	ds_read_b128 v[152:155], v112 offset:13152
	s_waitcnt lgkmcnt(6)
	v_mfma_f32_32x32x16_bf16 v[50:65], v[128:131], v[78:81], v[50:65]
	s_waitcnt lgkmcnt(5)
	v_mfma_f32_32x32x16_bf16 v[34:49], v[132:135], v[74:77], v[34:49]
	s_waitcnt lgkmcnt(4)
	v_mfma_f32_32x32x16_bf16 v[50:65], v[136:139], v[74:77], v[50:65]
	s_waitcnt lgkmcnt(3)
	v_mfma_f32_32x32x16_bf16 v[34:49], v[140:143], v[70:73], v[34:49]
	s_waitcnt lgkmcnt(2)
	v_mfma_f32_32x32x16_bf16 v[50:65], v[144:147], v[70:73], v[50:65]
	s_waitcnt lgkmcnt(1)
	v_mfma_f32_32x32x16_bf16 v[34:49], v[148:151], v[66:69], v[34:49]
	s_waitcnt lgkmcnt(0)
	v_mfma_f32_32x32x16_bf16 v[50:65], v[152:155], v[66:69], v[50:65]
	v_add_u32_e32 v122, 0x8800, v113
	v_add_u32_e32 v123, 0x9800, v113
	ds_read2_b64 v[166:169], v122 offset0:96 offset1:98
	ds_read2_b64 v[170:173], v123 offset0:128 offset1:130
	ds_read2_b64 v[174:177], v122 offset0:100 offset1:102
	ds_read2_b64 v[178:181], v123 offset0:132 offset1:134
	ds_read2_b64 v[182:185], v122 offset0:104 offset1:106
	ds_read2_b64 v[186:189], v123 offset0:136 offset1:138
	ds_read2_b64 v[190:193], v122 offset0:108 offset1:110
	ds_read2_b64 v[194:197], v123 offset0:140 offset1:142
	v_sub_f32_e32 v214, v214, v114
	v_sub_f32_e32 v215, v215, v114
	v_sub_f32_e32 v216, v216, v114
	v_sub_f32_e32 v217, v217, v114
	v_sub_f32_e32 v218, v218, v114
	v_sub_f32_e32 v219, v219, v114
	v_sub_f32_e32 v220, v220, v114
	v_sub_f32_e32 v221, v221, v114
	v_exp_f32_e32 v214, v214
	v_exp_f32_e32 v215, v215
	v_exp_f32_e32 v216, v216
	v_exp_f32_e32 v217, v217
	v_exp_f32_e32 v218, v218
	v_exp_f32_e32 v219, v219
	v_exp_f32_e32 v220, v220
	v_exp_f32_e32 v221, v221
	s_waitcnt lgkmcnt(0)
	v_mfma_f32_32x32x16_bf16 v[18:33], v[166:169], v[118:121], v[18:33]
	v_mfma_f32_32x32x16_bf16 v[2:17], v[170:173], v[118:121], v[2:17]
	v_cvt_pk_bf16_f32 v118, v214, v215
	v_cvt_pk_bf16_f32 v119, v216, v217
	v_cvt_pk_bf16_f32 v120, v218, v219
	v_cvt_pk_bf16_f32 v121, v220, v221
	v_add_f32_e32 v116, v116, v214
	v_add_f32_e32 v117, v117, v215
	v_add_f32_e32 v116, v116, v216
	v_add_f32_e32 v117, v117, v217
	v_add_f32_e32 v116, v116, v218
	v_add_f32_e32 v117, v117, v219
	v_add_f32_e32 v116, v116, v220
	v_add_f32_e32 v117, v117, v221
	v_mfma_f32_32x32x16_bf16 v[18:33], v[174:177], v[118:121], v[18:33]
	v_mfma_f32_32x32x16_bf16 v[2:17], v[178:181], v[118:121], v[2:17]
	v_sub_f32_e32 v222, v222, v114
	v_sub_f32_e32 v223, v223, v114
	v_sub_f32_e32 v224, v224, v114
	v_sub_f32_e32 v225, v225, v114
	v_sub_f32_e32 v226, v226, v114
	v_sub_f32_e32 v227, v227, v114
	v_sub_f32_e32 v228, v228, v114
	v_sub_f32_e32 v229, v229, v114
	v_exp_f32_e32 v222, v222
	v_exp_f32_e32 v223, v223
	v_exp_f32_e32 v224, v224
	v_exp_f32_e32 v225, v225
	v_exp_f32_e32 v226, v226
	v_exp_f32_e32 v227, v227
	v_exp_f32_e32 v228, v228
	v_exp_f32_e32 v229, v229
	v_cvt_pk_bf16_f32 v118, v222, v223
	v_cvt_pk_bf16_f32 v119, v224, v225
	v_cvt_pk_bf16_f32 v120, v226, v227
	v_cvt_pk_bf16_f32 v121, v228, v229
	v_add_f32_e32 v116, v116, v222
	v_add_f32_e32 v117, v117, v223
	v_add_f32_e32 v116, v116, v224
	v_add_f32_e32 v117, v117, v225
	v_add_f32_e32 v116, v116, v226
	v_add_f32_e32 v117, v117, v227
	v_add_f32_e32 v116, v116, v228
	v_add_f32_e32 v117, v117, v229
	v_mfma_f32_32x32x16_bf16 v[18:33], v[182:185], v[118:121], v[18:33]
	v_mfma_f32_32x32x16_bf16 v[2:17], v[186:189], v[118:121], v[2:17]
	v_sub_f32_e32 v230, v230, v114
	v_sub_f32_e32 v231, v231, v114
	v_sub_f32_e32 v232, v232, v114
	v_sub_f32_e32 v233, v233, v114
	v_sub_f32_e32 v234, v234, v114
	v_sub_f32_e32 v235, v235, v114
	v_sub_f32_e32 v236, v236, v114
	v_sub_f32_e32 v237, v237, v114
	v_exp_f32_e32 v230, v230
	v_exp_f32_e32 v231, v231
	v_exp_f32_e32 v232, v232
	v_exp_f32_e32 v233, v233
	v_exp_f32_e32 v234, v234
	v_exp_f32_e32 v235, v235
	v_exp_f32_e32 v236, v236
	v_exp_f32_e32 v237, v237
	v_cvt_pk_bf16_f32 v118, v230, v231
	v_cvt_pk_bf16_f32 v119, v232, v233
	v_cvt_pk_bf16_f32 v120, v234, v235
	v_cvt_pk_bf16_f32 v121, v236, v237
	v_add_f32_e32 v116, v116, v230
	v_add_f32_e32 v117, v117, v231
	v_add_f32_e32 v116, v116, v232
	v_add_f32_e32 v117, v117, v233
	v_add_f32_e32 v116, v116, v234
	v_add_f32_e32 v117, v117, v235
	v_add_f32_e32 v116, v116, v236
	v_add_f32_e32 v117, v117, v237
	v_mfma_f32_32x32x16_bf16 v[18:33], v[190:193], v[118:121], v[18:33]
	v_mfma_f32_32x32x16_bf16 v[2:17], v[194:197], v[118:121], v[2:17]
	v_add_f32_e32 v116, v116, v117
	v_add_f32_e32 v109, v109, v116
	s_branch .Lmax_S0

; __device__ __forceinline__ void attn_tile(int t, int buf, LAS unsigned char* lds, const bf16x8 (&qr)[4], float cq2, int qlo, int qpos, int q32, int hi,
;                                           float& mrun, float& lrun, f32x16& o0, f32x16& o1) {
;     const LAS float* c2s = (const LAS float*)(lds + AT_C2);
;     const LAS unsigned char* Kt = lds + AT_K + buf * AT_KB; const LAS unsigned char* Vt = lds + AT_VT + buf * AT_VB;
;     f32x16 s0, s1;
; #pragma unroll
;     for (int j = 0; j < 4; ++j) {
;         const f32x4 c0 = *(const LAS f32x4*)(c2s + 64 * t + 8 * j + 4 * hi), c1 = *(const LAS f32x4*)(c2s + 64 * t + 32 + 8 * j + 4 * hi);
; #pragma unroll
;         for (int e = 0; e < 4; ++e) { s0[4 * j + e] = c0[e]; s1[4 * j + e] = c1[e]; }
;     }
; #pragma unroll
;     for (int d0 = 0; d0 < 4; ++d0) {
;         const bf16x8 k0 = *(const LAS bf16x8*)(Kt + q32 * 144 + d0 * 32 + hi * 16);
;         const bf16x8 k1 = *(const LAS bf16x8*)(Kt + (32 + q32) * 144 + d0 * 32 + hi * 16);
;         s0 = __builtin_amdgcn_mfma_f32_32x32x16_bf16(k0, qr[d0], s0, 0, 0, 0);
;         s1 = __builtin_amdgcn_mfma_f32_32x32x16_bf16(k1, qr[d0], s1, 0, 0, 0);
;     }
;     if (64 * t + 63 > qlo) {
; #pragma unroll
;         for (int r = 0; r < 16; ++r) { const int kv = 64 * t + crow(r, hi); if (kv > qpos) s0[r] = -INFINITY; if (kv + 32 > qpos) s1[r] = -INFINITY; }
;     }
;     float mx = fmaxf(s0[0], s1[0]);
; #pragma unroll
;     for (int r = 1; r < 16; ++r) mx = fmaxf(mx, fmaxf(s0[r], s1[r]));
;     mx = fmaxf(mx, __shfl_xor(mx, 32));
;     const float mnew = fmaxf(mrun, mx);
;     if (__any(mnew > mrun)) {
;         const float alpha = fexp2(mrun - mnew); lrun *= alpha;
; #pragma unroll
;         for (int r = 0; r < 16; ++r) { o0[r] *= alpha; o1[r] *= alpha; }
;     }
;     mrun = mnew;
;     f32x2 ls2 = (f32x2){0.f, 0.f};
; #pragma unroll
;     for (int r = 0; r < 16; r += 2) {
;         const f32x2 d0 = (f32x2){s0[r], s0[r + 1]} - mnew, d1 = (f32x2){s1[r], s1[r + 1]} - mnew;
; __device__ __forceinline__ void attn_unit(const AttnJob& J, LAS unsigned char* lds) {
;     ...
;         if (t + 1 < J.NT) {
;             attn_stage(lds, 1, kB, vB);
;             __syncthreads();
;             if (t + 3 < J.NT) attn_load(J, t + 3, kB, vB);
;             if (active && 64 * (t + 1) <= qlo + 31) attn_tile(t + 1, 1, lds, qr, cq2, qlo, qpos, q32, hi, mrun, lrun, o0, o1);
.Lend_S0:
.Lslot_S1:
	s_waitcnt vmcnt(6)
	ds_write_b128 v156, v[90:93] offset:17664
	ds_write_b16 v157, v86 offset:26880
	ds_write_b16_d16_hi v157, v86 offset:27016
	ds_write_b16 v157, v87 offset:27152
	ds_write_b16_d16_hi v157, v87 offset:27288
	ds_write_b16 v157, v88 offset:27424
	ds_write_b16_d16_hi v157, v88 offset:27560
	ds_write_b16 v157, v89 offset:27696
	ds_write_b16_d16_hi v157, v89 offset:27832
	s_waitcnt lgkmcnt(0)
	s_barrier
	s_add_i32 s6, s22, 5
	s_lshl_b32 s6, s6, 18
	s_add_u32 s98, s8, s6
	s_addc_u32 s99, s9, 0
	global_load_dwordx4 v[90:93], v158, s[98:99] offset:1024
	s_sub_u32 s100, s98, 0x40000
	s_subb_u32 s101, s99, 0
	global_load_dwordx4 v[86:89], v158, s[100:101] offset:2048
	s_lshl_b32 s6, s22, 6
	s_add_i32 s6, s6, 64
	s_cmp_le_i32 s6, s23
	s_cbranch_scc0 .Lnoproc_S1
	ds_read_b128 v[124:127], v112 offset:17664
	ds_read_b128 v[206:209], v111 offset:256
	ds_read_b128 v[210:213], v111 offset:288
	ds_read_b128 v[214:217], v111 offset:320
	ds_read_b128 v[218:221], v111 offset:352
	ds_read_b128 v[128:131], v112 offset:22272
	ds_read_b128 v[222:225], v111 offset:384
	ds_read_b128 v[226:229], v111 offset:416
	ds_read_b128 v[230:233], v111 offset:448
	ds_read_b128 v[234:237], v111 offset:480
	ds_read_b128 v[132:135], v112 offset:17696
	ds_read_b128 v[136:139], v112 offset:22304
	ds_read_b128 v[140:143], v112 offset:17728
	ds_read_b128 v[144:147], v112 offset:22336
	s_cmp_eq_u32 s26, 0
	s_cbranch_scc1 .Lqkonly_S1
	v_sub_f32_e32 v34, v34, v114
	v_sub_f32_e32 v35, v35, v114
	v_sub_f32_e32 v36, v36, v114
	v_sub_f32_e32 v37, v37, v114
	v_sub_f32_e32 v38, v38, v114
	v_sub_f32_e32 v39, v39, v114
	v_sub_f32_e32 v40, v40, v114
	v_sub_f32_e32 v41, v41, v114
	v_exp_f32_e32 v34, v34
	v_exp_f32_e32 v35, v35
	v_exp_f32_e32 v36, v36
	v_exp_f32_e32 v37, v37
	v_exp_f32_e32 v38, v38
	v_exp_f32_e32 v39, v39
	v_exp_f32_e32 v40, v40
	v_exp_f32_e32 v41, v41
	v_cvt_pk_bf16_f32 v118, v34, v35
	v_cvt_pk_bf16_f32 v119, v36, v37
	v_cvt_pk_bf16_f32 v120, v38, v39
	v_cvt_pk_bf16_f32 v121, v40, v41
	v_add_f32_e32 v116, v34, v36
	v_add_f32_e32 v117, v35, v37
	v_add_f32_e32 v116, v116, v38
	v_add_f32_e32 v117, v117, v39
	v_add_f32_e32 v116, v116, v40
	v_add_f32_e32 v117, v117, v41
	s_waitcnt lgkmcnt(9)
	v_mfma_f32_32x32x16_bf16 v[206:221], v[124:127], v[78:81], v[206:221]
	ds_read_b128 v[148:151], v112 offset:17760
	ds_read_b128 v[152:155], v112 offset:22368
	s_waitcnt lgkmcnt(6)
	v_mfma_f32_32x32x16_bf16 v[222:237], v[128:131], v[78:81], v[222:237]
	s_waitcnt lgkmcnt(5)
	v_mfma_f32_32x32x16_bf16 v[206:221], v[132:135], v[74:77], v[206:221]
	s_waitcnt lgkmcnt(4)
	v_mfma_f32_32x32x16_bf16 v[222:237], v[136:139], v[74:77], v[222:237]
	s_waitcnt lgkmcnt(3)
	v_mfma_f32_32x32x16_bf16 v[206:221], v[140:143], v[70:73], v[206:221]
	s_waitcnt lgkmcnt(2)
	v_mfma_f32_32x32x16_bf16 v[222:237], v[144:147], v[70:73], v[222:237]
	s_waitcnt lgkmcnt(1)
	v_mfma_f32_32x32x16_bf16 v[206:221], v[148:151], v[66:69], v[206:221]
	s_waitcnt lgkmcnt(0)
	v_mfma_f32_32x32x16_bf16 v[222:237], v[152:155], v[66:69], v[222:237]
	v_add_u32_e32 v122, 0x6800, v113
	v_add_u32_e32 v123, 0x7800, v113
	ds_read2_b64 v[166:169], v122 offset0:32 offset1:34
	ds_read2_b64 v[170:173], v123 offset0:64 offset1:66
	ds_read2_b64 v[174:177], v122 offset0:36 offset1:38
	ds_read2_b64 v[178:181], v123 offset0:68 offset1:70
	ds_read2_b64 v[182:185], v122 offset0:40 offset1:42
	ds_read2_b64 v[186:189], v123 offset0:72 offset1:74
	ds_read2_b64 v[190:193], v122 offset0:44 offset1:46
	ds_read2_b64 v[194:197], v123 offset0:76 offset1:78
	v_sub_f32_e32 v42, v42, v114
	v_sub_f32_e32 v43, v43, v114
	v_sub_f32_e32 v44, v44, v114
	v_sub_f32_e32 v45, v45, v114
	v_sub_f32_e32 v46, v46, v114
	v_sub_f32_e32 v47, v47, v114
	v_sub_f32_e32 v48, v48, v114
	v_sub_f32_e32 v49, v49, v114
	v_exp_f32_e32 v42, v42
	v_exp_f32_e32 v43, v43
	v_exp_f32_e32 v44, v44
	v_exp_f32_e32 v45, v45
	v_exp_f32_e32 v46, v46
	v_exp_f32_e32 v47, v47
	v_exp_f32_e32 v48, v48
	v_exp_f32_e32 v49, v49
	s_waitcnt lgkmcnt(0)
	v_mfma_f32_32x32x16_bf16 v[18:33], v[166:169], v[118:121], v[18:33]
	v_mfma_f32_32x32x16_bf16 v[2:17], v[170:173], v[118:121], v[2:17]
	v_cvt_pk_bf16_f32 v118, v42, v43
	v_cvt_pk_bf16_f32 v119, v44, v45
	v_cvt_pk_bf16_f32 v120, v46, v47
	v_cvt_pk_bf16_f32 v121, v48, v49
	v_add_f32_e32 v116, v116, v42
	v_add_f32_e32 v117, v117, v43
	v_add_f32_e32 v116, v116, v44
	v_add_f32_e32 v117, v117, v45
	v_add_f32_e32 v116, v116, v46
	v_add_f32_e32 v117, v117, v47
	v_add_f32_e32 v116, v116, v48
	v_add_f32_e32 v117, v117, v49
	v_mfma_f32_32x32x16_bf16 v[18:33], v[174:177], v[118:121], v[18:33]
	v_mfma_f32_32x32x16_bf16 v[2:17], v[178:181], v[118:121], v[2:17]
	v_sub_f32_e32 v50, v50, v114
	v_sub_f32_e32 v51, v51, v114
	v_sub_f32_e32 v52, v52, v114
	v_sub_f32_e32 v53, v53, v114
	v_sub_f32_e32 v54, v54, v114
	v_sub_f32_e32 v55, v55, v114
	v_sub_f32_e32 v56, v56, v114
	v_sub_f32_e32 v57, v57, v114
	v_exp_f32_e32 v50, v50
	v_exp_f32_e32 v51, v51
	v_exp_f32_e32 v52, v52
	v_exp_f32_e32 v53, v53
	v_exp_f32_e32 v54, v54
	v_exp_f32_e32 v55, v55
	v_exp_f32_e32 v56, v56
	v_exp_f32_e32 v57, v57
	v_cvt_pk_bf16_f32 v118, v50, v51
	v_cvt_pk_bf16_f32 v119, v52, v53
	v_cvt_pk_bf16_f32 v120, v54, v55
	v_cvt_pk_bf16_f32 v121, v56, v57
	v_add_f32_e32 v116, v116, v50
	v_add_f32_e32 v117, v117, v51
	v_add_f32_e32 v116, v116, v52
	v_add_f32_e32 v117, v117, v53
	v_add_f32_e32 v116, v116, v54
	v_add_f32_e32 v117, v117, v55
	v_add_f32_e32 v116, v116, v56
	v_add_f32_e32 v117, v117, v57
	v_mfma_f32_32x32x16_bf16 v[18:33], v[182:185], v[118:121], v[18:33]
	v_mfma_f32_32x32x16_bf16 v[2:17], v[186:189], v[118:121], v[2:17]
	v_sub_f32_e32 v58, v58, v114
	v_sub_f32_e32 v59, v59, v114
	v_sub_f32_e32 v60, v60, v114
	v_sub_f32_e32 v61, v61, v114
	v_sub_f32_e32 v62, v62, v114
	v_sub_f32_e32 v63, v63, v114
	v_sub_f32_e32 v64, v64, v114
	v_sub_f32_e32 v65, v65, v114
	v_exp_f32_e32 v58, v58
	v_exp_f32_e32 v59, v59
	v_exp_f32_e32 v60, v60
	v_exp_f32_e32 v61, v61
	v_exp_f32_e32 v62, v62
	v_exp_f32_e32 v63, v63
	v_exp_f32_e32 v64, v64
	v_exp_f32_e32 v65, v65
	v_cvt_pk_bf16_f32 v118, v58, v59
	v_cvt_pk_bf16_f32 v119, v60, v61
	v_cvt_pk_bf16_f32 v120, v62, v63
	v_cvt_pk_bf16_f32 v121, v64, v65
	v_add_f32_e32 v116, v116, v58
	v_add_f32_e32 v117, v117, v59
	v_add_f32_e32 v116, v116, v60
	v_add_f32_e32 v117, v117, v61
	v_add_f32_e32 v116, v116, v62
	v_add_f32_e32 v117, v117, v63
	v_add_f32_e32 v116, v116, v64
	v_add_f32_e32 v117, v117, v65
	v_mfma_f32_32x32x16_bf16 v[18:33], v[190:193], v[118:121], v[18:33]
	v_mfma_f32_32x32x16_bf16 v[2:17], v[194:197], v[118:121], v[2:17]
	v_add_f32_e32 v116, v116, v117
	v_add_f32_e32 v109, v109, v116
	s_branch .Lmax_S1

; __device__ __forceinline__ void attn_tile(int t, int buf, LAS unsigned char* lds, const bf16x8 (&qr)[4], float cq2, int qlo, int qpos, int q32, int hi,
;                                           float& mrun, float& lrun, f32x16& o0, f32x16& o1) {
;     const LAS float* c2s = (const LAS float*)(lds + AT_C2);
;     const LAS unsigned char* Kt = lds + AT_K + buf * AT_KB; const LAS unsigned char* Vt = lds + AT_VT + buf * AT_VB;
;     f32x16 s0, s1;
; #pragma unroll
;     for (int j = 0; j < 4; ++j) {
;         const f32x4 c0 = *(const LAS f32x4*)(c2s + 64 * t + 8 * j + 4 * hi), c1 = *(const LAS f32x4*)(c2s + 64 * t + 32 + 8 * j + 4 * hi);
; #pragma unroll
;         for (int e = 0; e < 4; ++e) { s0[4 * j + e] = c0[e]; s1[4 * j + e] = c1[e]; }
;     }
; #pragma unroll
;     for (int d0 = 0; d0 < 4; ++d0) {
;         const bf16x8 k0 = *(const LAS bf16x8*)(Kt + q32 * 144 + d0 * 32 + hi * 16);
;         const bf16x8 k1 = *(const LAS bf16x8*)(Kt + (32 + q32) * 144 + d0 * 32 + hi * 16);
;         s0 = __builtin_amdgcn_mfma_f32_32x32x16_bf16(k0, qr[d0], s0, 0, 0, 0);
;         s1 = __builtin_amdgcn_mfma_f32_32x32x16_bf16(k1, qr[d0], s1, 0, 0, 0);
;     }
;     if (64 * t + 63 > qlo) {
; #pragma unroll
;         for (int r = 0; r < 16; ++r) { const int kv = 64 * t + crow(r, hi); if (kv > qpos) s0[r] = -INFINITY; if (kv + 32 > qpos) s1[r] = -INFINITY; }
;     }
;     float mx = fmaxf(s0[0], s1[0]);
; #pragma unroll
;     for (int r = 1; r < 16; ++r) mx = fmaxf(mx, fmaxf(s0[r], s1[r]));
;     mx = fmaxf(mx, __shfl_xor(mx, 32));
;     const float mnew = fmaxf(mrun, mx);
;     if (__any(mnew > mrun)) {
;         const float alpha = fexp2(mrun - mnew); lrun *= alpha;
; #pragma unroll
;         for (int r = 0; r < 16; ++r) { o0[r] *= alpha; o1[r] *= alpha; }
;     }
;     mrun = mnew;
;     f32x2 ls2 = (f32x2){0.f, 0.f};
; #pragma unroll
;     for (int r = 0; r < 16; r += 2) {
;         const f32x2 d0 = (f32x2){s0[r], s0[r + 1]} - mnew, d1 = (f32x2){s1[r], s1[r + 1]} - mnew;
; __device__ __forceinline__ void attn_unit(const AttnJob& J, LAS unsigned char* lds) {
;     ...
;     for (int t = 0; t < J.NT; t += 2) {
;         attn_stage(lds, 0, kA, vA);
;         __syncthreads();
;         if (t + 2 < J.NT) attn_load(J, t + 2, kA, vA);
;         if (active && 64 * t <= qlo + 31) attn_tile(t, 0, lds, qr, cq2, qlo, qpos, q32, hi, mrun, lrun, o0, o1);
.Lend_S1:
.Lslot_S2:
	s_waitcnt vmcnt(6)
	ds_write_b128 v156, v[238:241] offset:8448
	ds_write_b16 v157, v94 offset:35584
	ds_write_b16_d16_hi v157, v94 offset:35720
	ds_write_b16 v157, v95 offset:35856
	ds_write_b16_d16_hi v157, v95 offset:35992
	ds_write_b16 v157, v96 offset:36128
	ds_write_b16_d16_hi v157, v96 offset:36264
	ds_write_b16 v157, v97 offset:36400
	ds_write_b16_d16_hi v157, v97 offset:36536
	s_waitcnt lgkmcnt(0)
	s_barrier
	s_add_i32 s6, s22, 6
	s_lshl_b32 s6, s6, 18
	s_add_u32 s98, s8, s6
	s_addc_u32 s99, s9, 0
	global_load_dwordx4 v[238:241], v158, s[98:99] offset:1024
	s_sub_u32 s100, s98, 0x40000
	s_subb_u32 s101, s99, 0
	global_load_dwordx4 v[94:97], v158, s[100:101] offset:2048
	s_lshl_b32 s6, s22, 6
	s_add_i32 s6, s6, 128
	s_cmp_le_i32 s6, s23
	s_cbranch_scc0 .Lnoproc_S2
	ds_read_b128 v[124:127], v112 offset:8448
	ds_read_b128 v[34:37], v111 offset:512
	ds_read_b128 v[38:41], v111 offset:544
	ds_read_b128 v[42:45], v111 offset:576
	ds_read_b128 v[46:49], v111 offset:608
	ds_read_b128 v[128:131], v112 offset:13056
	ds_read_b128 v[50:53], v111 offset:640
	ds_read_b128 v[54:57], v111 offset:672
	ds_read_b128 v[58:61], v111 offset:704
	ds_read_b128 v[62:65], v111 offset:736
	ds_read_b128 v[132:135], v112 offset:8480
	ds_read_b128 v[136:139], v112 offset:13088
	ds_read_b128 v[140:143], v112 offset:8512
	ds_read_b128 v[144:147], v112 offset:13120
	s_cmp_eq_u32 s27, 0
	s_cbranch_scc1 .Lqkonly_S2
	v_sub_f32_e32 v206, v206, v114
	v_sub_f32_e32 v207, v207, v114
	v_sub_f32_e32 v208, v208, v114
	v_sub_f32_e32 v209, v209, v114
	v_sub_f32_e32 v210, v210, v114
	v_sub_f32_e32 v211, v211, v114
	v_sub_f32_e32 v212, v212, v114
	v_sub_f32_e32 v213, v213, v114
	v_exp_f32_e32 v206, v206
	v_exp_f32_e32 v207, v207
	v_exp_f32_e32 v208, v208
	v_exp_f32_e32 v209, v209
	v_exp_f32_e32 v210, v210
	v_exp_f32_e32 v211, v211
	v_exp_f32_e32 v212, v212
	v_exp_f32_e32 v213, v213
	v_cvt_pk_bf16_f32 v118, v206, v207
	v_cvt_pk_bf16_f32 v119, v208, v209
	v_cvt_pk_bf16_f32 v120, v210, v211
	v_cvt_pk_bf16_f32 v121, v212, v213
	v_add_f32_e32 v116, v206, v208
	v_add_f32_e32 v117, v207, v209
	v_add_f32_e32 v116, v116, v210
	v_add_f32_e32 v117, v117, v211
	v_add_f32_e32 v116, v116, v212
	v_add_f32_e32 v117, v117, v213
	s_waitcnt lgkmcnt(9)
	v_mfma_f32_32x32x16_bf16 v[34:49], v[124:127], v[78:81], v[34:49]
	ds_read_b128 v[148:151], v112 offset:8544
	ds_read_b128 v[152:155], v112 offset:13152
	s_waitcnt lgkmcnt(6)
	v_mfma_f32_32x32x16_bf16 v[50:65], v[128:131], v[78:81], v[50:65]
	s_waitcnt lgkmcnt(5)
	v_mfma_f32_32x32x16_bf16 v[34:49], v[132:135], v[74:77], v[34:49]
	s_waitcnt lgkmcnt(4)
	v_mfma_f32_32x32x16_bf16 v[50:65], v[136:139], v[74:77], v[50:65]
	s_waitcnt lgkmcnt(3)
	v_mfma_f32_32x32x16_bf16 v[34:49], v[140:143], v[70:73], v[34:49]
	s_waitcnt lgkmcnt(2)
	v_mfma_f32_32x32x16_bf16 v[50:65], v[144:147], v[70:73], v[50:65]
	s_waitcnt lgkmcnt(1)
	v_mfma_f32_32x32x16_bf16 v[34:49], v[148:151], v[66:69], v[34:49]
	s_waitcnt lgkmcnt(0)
	v_mfma_f32_32x32x16_bf16 v[50:65], v[152:155], v[66:69], v[50:65]
	v_add_u32_e32 v122, 0x8800, v113
	v_add_u32_e32 v123, 0x9800, v113
	ds_read2_b64 v[166:169], v122 offset0:96 offset1:98
	ds_read2_b64 v[170:173], v123 offset0:128 offset1:130
	ds_read2_b64 v[174:177], v122 offset0:100 offset1:102
	ds_read2_b64 v[178:181], v123 offset0:132 offset1:134
	ds_read2_b64 v[182:185], v122 offset0:104 offset1:106
	ds_read2_b64 v[186:189], v123 offset0:136 offset1:138
	ds_read2_b64 v[190:193], v122 offset0:108 offset1:110
	ds_read2_b64 v[194:197], v123 offset0:140 offset1:142
	v_sub_f32_e32 v214, v214, v114
	v_sub_f32_e32 v215, v215, v114
	v_sub_f32_e32 v216, v216, v114
	v_sub_f32_e32 v217, v217, v114
	v_sub_f32_e32 v218, v218, v114
	v_sub_f32_e32 v219, v219, v114
	v_sub_f32_e32 v220, v220, v114
	v_sub_f32_e32 v221, v221, v114
	v_exp_f32_e32 v214, v214
	v_exp_f32_e32 v215, v215
	v_exp_f32_e32 v216, v216
	v_exp_f32_e32 v217, v217
	v_exp_f32_e32 v218, v218
	v_exp_f32_e32 v219, v219
	v_exp_f32_e32 v220, v220
	v_exp_f32_e32 v221, v221
	s_waitcnt lgkmcnt(0)
	v_mfma_f32_32x32x16_bf16 v[18:33], v[166:169], v[118:121], v[18:33]
	v_mfma_f32_32x32x16_bf16 v[2:17], v[170:173], v[118:121], v[2:17]
	v_cvt_pk_bf16_f32 v118, v214, v215
	v_cvt_pk_bf16_f32 v119, v216, v217
	v_cvt_pk_bf16_f32 v120, v218, v219
	v_cvt_pk_bf16_f32 v121, v220, v221
	v_add_f32_e32 v116, v116, v214
	v_add_f32_e32 v117, v117, v215
	v_add_f32_e32 v116, v116, v216
	v_add_f32_e32 v117, v117, v217
	v_add_f32_e32 v116, v116, v218
	v_add_f32_e32 v117, v117, v219
	v_add_f32_e32 v116, v116, v220
	v_add_f32_e32 v117, v117, v221
	v_mfma_f32_32x32x16_bf16 v[18:33], v[174:177], v[118:121], v[18:33]
	v_mfma_f32_32x32x16_bf16 v[2:17], v[178:181], v[118:121], v[2:17]
	v_sub_f32_e32 v222, v222, v114
	v_sub_f32_e32 v223, v223, v114
	v_sub_f32_e32 v224, v224, v114
	v_sub_f32_e32 v225, v225, v114
	v_sub_f32_e32 v226, v226, v114
	v_sub_f32_e32 v227, v227, v114
	v_sub_f32_e32 v228, v228, v114
	v_sub_f32_e32 v229, v229, v114
	v_exp_f32_e32 v222, v222
	v_exp_f32_e32 v223, v223
	v_exp_f32_e32 v224, v224
	v_exp_f32_e32 v225, v225
	v_exp_f32_e32 v226, v226
	v_exp_f32_e32 v227, v227
	v_exp_f32_e32 v228, v228
	v_exp_f32_e32 v229, v229
	v_cvt_pk_bf16_f32 v118, v222, v223
	v_cvt_pk_bf16_f32 v119, v224, v225
	v_cvt_pk_bf16_f32 v120, v226, v227
	v_cvt_pk_bf16_f32 v121, v228, v229
	v_add_f32_e32 v116, v116, v222
	v_add_f32_e32 v117, v117, v223
	v_add_f32_e32 v116, v116, v224
	v_add_f32_e32 v117, v117, v225
	v_add_f32_e32 v116, v116, v226
	v_add_f32_e32 v117, v117, v227
	v_add_f32_e32 v116, v116, v228
	v_add_f32_e32 v117, v117, v229
	v_mfma_f32_32x32x16_bf16 v[18:33], v[182:185], v[118:121], v[18:33]
	v_mfma_f32_32x32x16_bf16 v[2:17], v[186:189], v[118:121], v[2:17]
	v_sub_f32_e32 v230, v230, v114
	v_sub_f32_e32 v231, v231, v114
	v_sub_f32_e32 v232, v232, v114
	v_sub_f32_e32 v233, v233, v114
	v_sub_f32_e32 v234, v234, v114
	v_sub_f32_e32 v235, v235, v114
	v_sub_f32_e32 v236, v236, v114
	v_sub_f32_e32 v237, v237, v114
	v_exp_f32_e32 v230, v230
	v_exp_f32_e32 v231, v231
	v_exp_f32_e32 v232, v232
	v_exp_f32_e32 v233, v233
	v_exp_f32_e32 v234, v234
	v_exp_f32_e32 v235, v235
	v_exp_f32_e32 v236, v236
	v_exp_f32_e32 v237, v237
	v_cvt_pk_bf16_f32 v118, v230, v231
	v_cvt_pk_bf16_f32 v119, v232, v233
	v_cvt_pk_bf16_f32 v120, v234, v235
	v_cvt_pk_bf16_f32 v121, v236, v237
	v_add_f32_e32 v116, v116, v230
	v_add_f32_e32 v117, v117, v231
	v_add_f32_e32 v116, v116, v232
	v_add_f32_e32 v117, v117, v233
	v_add_f32_e32 v116, v116, v234
	v_add_f32_e32 v117, v117, v235
	v_add_f32_e32 v116, v116, v236
	v_add_f32_e32 v117, v117, v237
	v_mfma_f32_32x32x16_bf16 v[18:33], v[190:193], v[118:121], v[18:33]
	v_mfma_f32_32x32x16_bf16 v[2:17], v[194:197], v[118:121], v[2:17]
	v_add_f32_e32 v116, v116, v117
	v_add_f32_e32 v109, v109, v116
	s_branch .Lmax_S2

; __device__ __forceinline__ void attn_tile(int t, int buf, LAS unsigned char* lds, const bf16x8 (&qr)[4], float cq2, int qlo, int qpos, int q32, int hi,
;                                           float& mrun, float& lrun, f32x16& o0, f32x16& o1) {
;     const LAS float* c2s = (const LAS float*)(lds + AT_C2);
;     const LAS unsigned char* Kt = lds + AT_K + buf * AT_KB; const LAS unsigned char* Vt = lds + AT_VT + buf * AT_VB;
;     f32x16 s0, s1;
; #pragma unroll
;     for (int j = 0; j < 4; ++j) {
;         const f32x4 c0 = *(const LAS f32x4*)(c2s + 64 * t + 8 * j + 4 * hi), c1 = *(const LAS f32x4*)(c2s + 64 * t + 32 + 8 * j + 4 * hi);
; #pragma unroll
;         for (int e = 0; e < 4; ++e) { s0[4 * j + e] = c0[e]; s1[4 * j + e] = c1[e]; }
;     }
; #pragma unroll
;     for (int d0 = 0; d0 < 4; ++d0) {
;         const bf16x8 k0 = *(const LAS bf16x8*)(Kt + q32 * 144 + d0 * 32 + hi * 16);
;         const bf16x8 k1 = *(const LAS bf16x8*)(Kt + (32 + q32) * 144 + d0 * 32 + hi * 16);
;         s0 = __builtin_amdgcn_mfma_f32_32x32x16_bf16(k0, qr[d0], s0, 0, 0, 0);
;         s1 = __builtin_amdgcn_mfma_f32_32x32x16_bf16(k1, qr[d0], s1, 0, 0, 0);
;     }
;     if (64 * t + 63 > qlo) {
; #pragma unroll
;         for (int r = 0; r < 16; ++r) { const int kv = 64 * t + crow(r, hi); if (kv > qpos) s0[r] = -INFINITY; if (kv + 32 > qpos) s1[r] = -INFINITY; }
;     }
;     float mx = fmaxf(s0[0], s1[0]);
; #pragma unroll
;     for (int r = 1; r < 16; ++r) mx = fmaxf(mx, fmaxf(s0[r], s1[r]));
;     mx = fmaxf(mx, __shfl_xor(mx, 32));
;     const float mnew = fmaxf(mrun, mx);
;     if (__any(mnew > mrun)) {
;         const float alpha = fexp2(mrun - mnew); lrun *= alpha;
; #pragma unroll
;         for (int r = 0; r < 16; ++r) { o0[r] *= alpha; o1[r] *= alpha; }
;     }
;     mrun = mnew;
;     f32x2 ls2 = (f32x2){0.f, 0.f};
; #pragma unroll
;     for (int r = 0; r < 16; r += 2) {
;         const f32x2 d0 = (f32x2){s0[r], s0[r + 1]} - mnew, d1 = (f32x2){s1[r], s1[r + 1]} - mnew;
; __device__ __forceinline__ void attn_unit(const AttnJob& J, LAS unsigned char* lds) {
;     ...
;         if (t + 1 < J.NT) {
;             attn_stage(lds, 1, kB, vB);
;             __syncthreads();
;             if (t + 3 < J.NT) attn_load(J, t + 3, kB, vB);
;             if (active && 64 * (t + 1) <= qlo + 31) attn_tile(t + 1, 1, lds, qr, cq2, qlo, qpos, q32, hi, mrun, lrun, o0, o1);
.Lend_S2:
.Lslot_S3:
	s_waitcnt vmcnt(6)
	ds_write_b128 v156, v[246:249] offset:17664
	ds_write_b16 v157, v242 offset:26880
	ds_write_b16_d16_hi v157, v242 offset:27016
	ds_write_b16 v157, v243 offset:27152
	ds_write_b16_d16_hi v157, v243 offset:27288
	ds_write_b16 v157, v244 offset:27424
	ds_write_b16_d16_hi v157, v244 offset:27560
	ds_write_b16 v157, v245 offset:27696
	ds_write_b16_d16_hi v157, v245 offset:27832
	s_waitcnt lgkmcnt(0)
	s_barrier
	s_add_i32 s6, s22, 7
	s_lshl_b32 s6, s6, 18
	s_add_u32 s98, s8, s6
	s_addc_u32 s99, s9, 0
	global_load_dwordx4 v[246:249], v158, s[98:99] offset:1024
	s_sub_u32 s100, s98, 0x40000
	s_subb_u32 s101, s99, 0
	global_load_dwordx4 v[242:245], v158, s[100:101] offset:2048
	s_lshl_b32 s6, s22, 6
	s_add_i32 s6, s6, 192
	s_cmp_le_i32 s6, s23
	s_cbranch_scc0 .Lnoproc_S3
	ds_read_b128 v[124:127], v112 offset:17664
	ds_read_b128 v[206:209], v111 offset:768
	ds_read_b128 v[210:213], v111 offset:800
	ds_read_b128 v[214:217], v111 offset:832
	ds_read_b128 v[218:221], v111 offset:864
	ds_read_b128 v[128:131], v112 offset:22272
	ds_read_b128 v[222:225], v111 offset:896
	ds_read_b128 v[226:229], v111 offset:928
	ds_read_b128 v[230:233], v111 offset:960
	ds_read_b128 v[234:237], v111 offset:992
	ds_read_b128 v[132:135], v112 offset:17696
	ds_read_b128 v[136:139], v112 offset:22304
	ds_read_b128 v[140:143], v112 offset:17728
	ds_read_b128 v[144:147], v112 offset:22336
	s_cmp_eq_u32 s26, 0
	s_cbranch_scc1 .Lqkonly_S3
	v_sub_f32_e32 v34, v34, v114
	v_sub_f32_e32 v35, v35, v114
	v_sub_f32_e32 v36, v36, v114
	v_sub_f32_e32 v37, v37, v114
	v_sub_f32_e32 v38, v38, v114
	v_sub_f32_e32 v39, v39, v114
	v_sub_f32_e32 v40, v40, v114
	v_sub_f32_e32 v41, v41, v114
	v_exp_f32_e32 v34, v34
	v_exp_f32_e32 v35, v35
	v_exp_f32_e32 v36, v36
	v_exp_f32_e32 v37, v37
	v_exp_f32_e32 v38, v38
	v_exp_f32_e32 v39, v39
	v_exp_f32_e32 v40, v40
	v_exp_f32_e32 v41, v41
	v_cvt_pk_bf16_f32 v118, v34, v35
	v_cvt_pk_bf16_f32 v119, v36, v37
	v_cvt_pk_bf16_f32 v120, v38, v39
	v_cvt_pk_bf16_f32 v121, v40, v41
	v_add_f32_e32 v116, v34, v36
	v_add_f32_e32 v117, v35, v37
	v_add_f32_e32 v116, v116, v38
	v_add_f32_e32 v117, v117, v39
	v_add_f32_e32 v116, v116, v40
	v_add_f32_e32 v117, v117, v41
	s_waitcnt lgkmcnt(9)
	v_mfma_f32_32x32x16_bf16 v[206:221], v[124:127], v[78:81], v[206:221]
	ds_read_b128 v[148:151], v112 offset:17760
	ds_read_b128 v[152:155], v112 offset:22368
	s_waitcnt lgkmcnt(6)
	v_mfma_f32_32x32x16_bf16 v[222:237], v[128:131], v[78:81], v[222:237]
	s_waitcnt lgkmcnt(5)
	v_mfma_f32_32x32x16_bf16 v[206:221], v[132:135], v[74:77], v[206:221]
	s_waitcnt lgkmcnt(4)
	v_mfma_f32_32x32x16_bf16 v[222:237], v[136:139], v[74:77], v[222:237]
	s_waitcnt lgkmcnt(3)
	v_mfma_f32_32x32x16_bf16 v[206:221], v[140:143], v[70:73], v[206:221]
	s_waitcnt lgkmcnt(2)
	v_mfma_f32_32x32x16_bf16 v[222:237], v[144:147], v[70:73], v[222:237]
	s_waitcnt lgkmcnt(1)
	v_mfma_f32_32x32x16_bf16 v[206:221], v[148:151], v[66:69], v[206:221]
	s_waitcnt lgkmcnt(0)
	v_mfma_f32_32x32x16_bf16 v[222:237], v[152:155], v[66:69], v[222:237]
	v_add_u32_e32 v122, 0x6800, v113
	v_add_u32_e32 v123, 0x7800, v113
	ds_read2_b64 v[166:169], v122 offset0:32 offset1:34
	ds_read2_b64 v[170:173], v123 offset0:64 offset1:66
	ds_read2_b64 v[174:177], v122 offset0:36 offset1:38
	ds_read2_b64 v[178:181], v123 offset0:68 offset1:70
	ds_read2_b64 v[182:185], v122 offset0:40 offset1:42
	ds_read2_b64 v[186:189], v123 offset0:72 offset1:74
	ds_read2_b64 v[190:193], v122 offset0:44 offset1:46
	ds_read2_b64 v[194:197], v123 offset0:76 offset1:78
	v_sub_f32_e32 v42, v42, v114
	v_sub_f32_e32 v43, v43, v114
	v_sub_f32_e32 v44, v44, v114
	v_sub_f32_e32 v45, v45, v114
	v_sub_f32_e32 v46, v46, v114
	v_sub_f32_e32 v47, v47, v114
	v_sub_f32_e32 v48, v48, v114
	v_sub_f32_e32 v49, v49, v114
	v_exp_f32_e32 v42, v42
	v_exp_f32_e32 v43, v43
	v_exp_f32_e32 v44, v44
	v_exp_f32_e32 v45, v45
	v_exp_f32_e32 v46, v46
	v_exp_f32_e32 v47, v47
	v_exp_f32_e32 v48, v48
	v_exp_f32_e32 v49, v49
	s_waitcnt lgkmcnt(0)
	v_mfma_f32_32x32x16_bf16 v[18:33], v[166:169], v[118:121], v[18:33]
	v_mfma_f32_32x32x16_bf16 v[2:17], v[170:173], v[118:121], v[2:17]
	v_cvt_pk_bf16_f32 v118, v42, v43
	v_cvt_pk_bf16_f32 v119, v44, v45
	v_cvt_pk_bf16_f32 v120, v46, v47
	v_cvt_pk_bf16_f32 v121, v48, v49
	v_add_f32_e32 v116, v116, v42
	v_add_f32_e32 v117, v117, v43
	v_add_f32_e32 v116, v116, v44
	v_add_f32_e32 v117, v117, v45
	v_add_f32_e32 v116, v116, v46
	v_add_f32_e32 v117, v117, v47
	v_add_f32_e32 v116, v116, v48
	v_add_f32_e32 v117, v117, v49
	v_mfma_f32_32x32x16_bf16 v[18:33], v[174:177], v[118:121], v[18:33]
	v_mfma_f32_32x32x16_bf16 v[2:17], v[178:181], v[118:121], v[2:17]
	v_sub_f32_e32 v50, v50, v114
	v_sub_f32_e32 v51, v51, v114
	v_sub_f32_e32 v52, v52, v114
	v_sub_f32_e32 v53, v53, v114
	v_sub_f32_e32 v54, v54, v114
	v_sub_f32_e32 v55, v55, v114
	v_sub_f32_e32 v56, v56, v114
	v_sub_f32_e32 v57, v57, v114
	v_exp_f32_e32 v50, v50
	v_exp_f32_e32 v51, v51
	v_exp_f32_e32 v52, v52
	v_exp_f32_e32 v53, v53
	v_exp_f32_e32 v54, v54
	v_exp_f32_e32 v55, v55
	v_exp_f32_e32 v56, v56
	v_exp_f32_e32 v57, v57
	v_cvt_pk_bf16_f32 v118, v50, v51
	v_cvt_pk_bf16_f32 v119, v52, v53
	v_cvt_pk_bf16_f32 v120, v54, v55
	v_cvt_pk_bf16_f32 v121, v56, v57
	v_add_f32_e32 v116, v116, v50
	v_add_f32_e32 v117, v117, v51
	v_add_f32_e32 v116, v116, v52
	v_add_f32_e32 v117, v117, v53
	v_add_f32_e32 v116, v116, v54
	v_add_f32_e32 v117, v117, v55
	v_add_f32_e32 v116, v116, v56
	v_add_f32_e32 v117, v117, v57
	v_mfma_f32_32x32x16_bf16 v[18:33], v[182:185], v[118:121], v[18:33]
	v_mfma_f32_32x32x16_bf16 v[2:17], v[186:189], v[118:121], v[2:17]
	v_sub_f32_e32 v58, v58, v114
	v_sub_f32_e32 v59, v59, v114
	v_sub_f32_e32 v60, v60, v114
	v_sub_f32_e32 v61, v61, v114
	v_sub_f32_e32 v62, v62, v114
	v_sub_f32_e32 v63, v63, v114
	v_sub_f32_e32 v64, v64, v114
	v_sub_f32_e32 v65, v65, v114
	v_exp_f32_e32 v58, v58
	v_exp_f32_e32 v59, v59
	v_exp_f32_e32 v60, v60
	v_exp_f32_e32 v61, v61
	v_exp_f32_e32 v62, v62
	v_exp_f32_e32 v63, v63
	v_exp_f32_e32 v64, v64
	v_exp_f32_e32 v65, v65
	v_cvt_pk_bf16_f32 v118, v58, v59
	v_cvt_pk_bf16_f32 v119, v60, v61
	v_cvt_pk_bf16_f32 v120, v62, v63
	v_cvt_pk_bf16_f32 v121, v64, v65
	v_add_f32_e32 v116, v116, v58
	v_add_f32_e32 v117, v117, v59
	v_add_f32_e32 v116, v116, v60
	v_add_f32_e32 v117, v117, v61
	v_add_f32_e32 v116, v116, v62
	v_add_f32_e32 v117, v117, v63
	v_add_f32_e32 v116, v116, v64
	v_add_f32_e32 v117, v117, v65
	v_mfma_f32_32x32x16_bf16 v[18:33], v[190:193], v[118:121], v[18:33]
	v_mfma_f32_32x32x16_bf16 v[2:17], v[194:197], v[118:121], v[2:17]
	v_add_f32_e32 v116, v116, v117
	v_add_f32_e32 v109, v109, v116
	s_branch .Lmax_S3

; __device__ __forceinline__ void attn_tile(int t, int buf, LAS unsigned char* lds, const bf16x8 (&qr)[4], float cq2, int qlo, int qpos, int q32, int hi,
;                                           float& mrun, float& lrun, f32x16& o0, f32x16& o1) {
;     ...
;     f32x2 ls2 = (f32x2){0.f, 0.f};
; #pragma unroll
;     for (int r = 0; r < 16; r += 2) {
;         const f32x2 d0 = (f32x2){s0[r], s0[r + 1]} - mnew, d1 = (f32x2){s1[r], s1[r + 1]} - mnew;
;         f32x2 e0, e1; e0.x = fexp2(d0.x); e0.y = fexp2(d0.y); e1.x = fexp2(d1.x); e1.y = fexp2(d1.y);
;         s0[r] = e0.x; s0[r + 1] = e0.y; s1[r] = e1.x; s1[r + 1] = e1.y;
;         ls2 += e0 + e1;
;     }
;     lrun += ls2.x + ls2.y;
; #pragma unroll
;     for (int p = 0; p < 2; ++p)
; #pragma unroll
;         for (int sx = 0; sx < 2; ++sx) {
;             u32x4 pw;
;             if (p == 0) pw = (u32x4){pk_bf16(s0[8 * sx + 0], s0[8 * sx + 1]), pk_bf16(s0[8 * sx + 2], s0[8 * sx + 3]), pk_bf16(s0[8 * sx + 4], s0[8 * sx + 5]), pk_bf16(s0[8 * sx + 6], s0[8 * sx + 7])};
;             else        pw = (u32x4){pk_bf16(s1[8 * sx + 0], s1[8 * sx + 1]), pk_bf16(s1[8 * sx + 2], s1[8 * sx + 3]), pk_bf16(s1[8 * sx + 4], s1[8 * sx + 5]), pk_bf16(s1[8 * sx + 6], s1[8 * sx + 7])};
;             const bf16x8 pf = __builtin_bit_cast(bf16x8, pw);
;             const int ko = (32 * p + 16 * sx + 4 * hi) * 2;
;             const u32x2 a0 = *(const LAS u32x2*)(Vt + q32 * 136 + ko), a1 = *(const LAS u32x2*)(Vt + q32 * 136 + ko + 16);
;             const u32x2 b0 = *(const LAS u32x2*)(Vt + (32 + q32) * 136 + ko), b1 = *(const LAS u32x2*)(Vt + (32 + q32) * 136 + ko + 16);
;             const bf16x8 vf0 = __builtin_bit_cast(bf16x8, (u32x4){a0.x, a0.y, a1.x, a1.y});
; __device__ __forceinline__ void attn_unit(const AttnJob& J, LAS unsigned char* lds) {
;     ...
;     for (int t = 0; t < J.NT; t += 2) {
;         attn_stage(lds, 0, kA, vA);
;         __syncthreads();
;         if (t + 2 < J.NT) attn_load(J, t + 2, kA, vA);
;         if (active && 64 * t <= qlo + 31) attn_tile(t, 0, lds, qr, cq2, qlo, qpos, q32, hi, mrun, lrun, o0, o1);
;         if (t + 1 < J.NT) {
;             attn_stage(lds, 1, kB, vB);
;             __syncthreads();
;             if (t + 3 < J.NT) attn_load(J, t + 3, kB, vB);
;             if (active && 64 * (t + 1) <= qlo + 31) attn_tile(t + 1, 1, lds, qr, cq2, qlo, qpos, q32, hi, mrun, lrun, o0, o1);
;         }
;     }
.Lend_S3:
	s_add_i32 s22, s22, 4
	v_add_u32_e32 v111, 0x400, v111
	s_cmp_lt_u32 s22, s20
	s_cbranch_scc1 .Lslot_S0
	s_waitcnt vmcnt(0)
	ds_write_b16 v157, v160 offset:35584
	ds_write_b16_d16_hi v157, v160 offset:35720
	ds_write_b16 v157, v161 offset:35856
	ds_write_b16_d16_hi v157, v161 offset:35992
	ds_write_b16 v157, v162 offset:36128
	ds_write_b16_d16_hi v157, v162 offset:36264
	ds_write_b16 v157, v163 offset:36400
	ds_write_b16_d16_hi v157, v163 offset:36536
	s_waitcnt lgkmcnt(0)
	s_barrier
	s_cmp_eq_u32 s27, 0
	s_cbranch_scc1 .LBB0_663
	v_add_u32_e32 v122, 0x8800, v113
	v_add_u32_e32 v123, 0x9800, v113
	ds_read2_b64 v[166:169], v122 offset0:96 offset1:98
	ds_read2_b64 v[170:173], v123 offset0:128 offset1:130
	ds_read2_b64 v[174:177], v122 offset0:100 offset1:102
	ds_read2_b64 v[178:181], v123 offset0:132 offset1:134
	ds_read2_b64 v[182:185], v122 offset0:104 offset1:106
	ds_read2_b64 v[186:189], v123 offset0:136 offset1:138
	ds_read2_b64 v[190:193], v122 offset0:108 offset1:110
	ds_read2_b64 v[194:197], v123 offset0:140 offset1:142
	v_sub_f32_e32 v206, v206, v114
	v_sub_f32_e32 v207, v207, v114
	v_sub_f32_e32 v208, v208, v114
	v_sub_f32_e32 v209, v209, v114
	v_sub_f32_e32 v210, v210, v114
	v_sub_f32_e32 v211, v211, v114
	v_sub_f32_e32 v212, v212, v114
	v_sub_f32_e32 v213, v213, v114
	v_exp_f32_e32 v206, v206
	v_exp_f32_e32 v207, v207
	v_exp_f32_e32 v208, v208
	v_exp_f32_e32 v209, v209
	v_exp_f32_e32 v210, v210
	v_exp_f32_e32 v211, v211
	v_exp_f32_e32 v212, v212
	v_exp_f32_e32 v213, v213
	v_cvt_pk_bf16_f32 v118, v206, v207
	v_cvt_pk_bf16_f32 v119, v208, v209
	v_cvt_pk_bf16_f32 v120, v210, v211
	v_cvt_pk_bf16_f32 v121, v212, v213
	v_add_f32_e32 v116, v206, v208
	v_add_f32_e32 v117, v207, v209
	v_add_f32_e32 v116, v116, v210
	v_add_f32_e32 v117, v117, v211
	v_add_f32_e32 v116, v116, v212
	v_add_f32_e32 v117, v117, v213
	s_waitcnt lgkmcnt(0)
	v_mfma_f32_32x32x16_bf16 v[18:33], v[166:169], v[118:121], v[18:33]
	v_mfma_f32_32x32x16_bf16 v[2:17], v[170:173], v[118:121], v[2:17]
	v_sub_f32_e32 v214, v214, v114
	v_sub_f32_e32 v215, v215, v114
	v_sub_f32_e32 v216, v216, v114
	v_sub_f32_e32 v217, v217, v114
	v_sub_f32_e32 v218, v218, v114
	v_sub_f32_e32 v219, v219, v114
	v_sub_f32_e32 v220, v220, v114
	v_sub_f32_e32 v221, v221, v114
	v_exp_f32_e32 v214, v214
	v_exp_f32_e32 v215, v215
	v_exp_f32_e32 v216, v216
	v_exp_f32_e32 v217, v217
	v_exp_f32_e32 v218, v218
	v_exp_f32_e32 v219, v219
	v_exp_f32_e32 v220, v220
	v_exp_f32_e32 v221, v221
	v_cvt_pk_bf16_f32 v118, v214, v215
	v_cvt_pk_bf16_f32 v119, v216, v217
	v_cvt_pk_bf16_f32 v120, v218, v219
	v_cvt_pk_bf16_f32 v121, v220, v221
	v_add_f32_e32 v116, v116, v214
	v_add_f32_e32 v117, v117, v215
	v_add_f32_e32 v116, v116, v216
	v_add_f32_e32 v117, v117, v217
	v_add_f32_e32 v116, v116, v218
	v_add_f32_e32 v117, v117, v219
	v_add_f32_e32 v116, v116, v220
	v_add_f32_e32 v117, v117, v221
	v_mfma_f32_32x32x16_bf16 v[18:33], v[174:177], v[118:121], v[18:33]
	v_mfma_f32_32x32x16_bf16 v[2:17], v[178:181], v[118:121], v[2:17]
	v_sub_f32_e32 v222, v222, v114
	v_sub_f32_e32 v223, v223, v114
	v_sub_f32_e32 v224, v224, v114
	v_sub_f32_e32 v225, v225, v114
	v_sub_f32_e32 v226, v226, v114
	v_sub_f32_e32 v227, v227, v114
	v_sub_f32_e32 v228, v228, v114
	v_sub_f32_e32 v229, v229, v114
	v_exp_f32_e32 v222, v222
	v_exp_f32_e32 v223, v223
	v_exp_f32_e32 v224, v224
	v_exp_f32_e32 v225, v225
	v_exp_f32_e32 v226, v226
	v_exp_f32_e32 v227, v227
	v_exp_f32_e32 v228, v228
	v_exp_f32_e32 v229, v229
	v_cvt_pk_bf16_f32 v118, v222, v223
	v_cvt_pk_bf16_f32 v119, v224, v225
	v_cvt_pk_bf16_f32 v120, v226, v227
	v_cvt_pk_bf16_f32 v121, v228, v229
	v_add_f32_e32 v116, v116, v222
	v_add_f32_e32 v117, v117, v223
	v_add_f32_e32 v116, v116, v224
	v_add_f32_e32 v117, v117, v225
	v_add_f32_e32 v116, v116, v226
	v_add_f32_e32 v117, v117, v227
	v_add_f32_e32 v116, v116, v228
	v_add_f32_e32 v117, v117, v229
	v_mfma_f32_32x32x16_bf16 v[18:33], v[182:185], v[118:121], v[18:33]
	v_mfma_f32_32x32x16_bf16 v[2:17], v[186:189], v[118:121], v[2:17]
	v_sub_f32_e32 v230, v230, v114
	v_sub_f32_e32 v231, v231, v114
	v_sub_f32_e32 v232, v232, v114
	v_sub_f32_e32 v233, v233, v114
	v_sub_f32_e32 v234, v234, v114
	v_sub_f32_e32 v235, v235, v114
	v_sub_f32_e32 v236, v236, v114
	v_sub_f32_e32 v237, v237, v114
	v_exp_f32_e32 v230, v230
	v_exp_f32_e32 v231, v231
	v_exp_f32_e32 v232, v232
	v_exp_f32_e32 v233, v233
	v_exp_f32_e32 v234, v234
	v_exp_f32_e32 v235, v235
	v_exp_f32_e32 v236, v236
	v_exp_f32_e32 v237, v237
	v_cvt_pk_bf16_f32 v118, v230, v231
	v_cvt_pk_bf16_f32 v119, v232, v233
	v_cvt_pk_bf16_f32 v120, v234, v235
	v_cvt_pk_bf16_f32 v121, v236, v237
	v_add_f32_e32 v116, v116, v230
	v_add_f32_e32 v117, v117, v231
	v_add_f32_e32 v116, v116, v232
	v_add_f32_e32 v117, v117, v233
	v_add_f32_e32 v116, v116, v234
	v_add_f32_e32 v117, v117, v235
	v_add_f32_e32 v116, v116, v236
	v_add_f32_e32 v117, v117, v237
	v_mfma_f32_32x32x16_bf16 v[18:33], v[190:193], v[118:121], v[18:33]
	v_mfma_f32_32x32x16_bf16 v[2:17], v[194:197], v[118:121], v[2:17]
	v_add_f32_e32 v116, v116, v117
	v_add_f32_e32 v109, v109, v116
